# split-K MLP2 layer-0 GEMM moved from the compiler loop to the 3-stage direct-to-LDS ring (variable k-tile count, k offset and next-item bases taken from the item prologue)
# speedup vs baseline: 1.1217x; 1.0143x over previous
.LBB0_842:
	s_sub_i32 s27, s33, s0
	s_cmp_gt_i32 s26, 1
	s_cselect_b64 s[2:3], -1, 0
	s_cmp_lt_i32 s26, 2
	s_cselect_b64 s[4:5], -1, 0
	s_mul_i32 s30, s26, s0
	s_cmp_eq_u32 s26, 1
	s_ff1_i32_b32 s0, s26
	v_and_b32_e32 v5, 15, v0
	s_cselect_b64 s[6:7], -1, 0
	s_lshr_b32 s34, 64, s0
	v_lshlrev_b32_e32 v2, 4, v0
	v_readlane_b32 s0, v251, 56
	v_ashrrev_i32_e32 v1, 7, v0
	v_bfe_u32 v6, v0, 4, 2
	v_and_b32_e32 v168, 0x70, v2
	v_mov_b32_e32 v169, 0
	v_readlane_b32 s1, v251, 57
	v_lshlrev_b32_e32 v5, 7, v5
	v_bfe_u32 v9, v0, 1, 3
	v_lshl_add_u64 v[172:173], s[0:1], 0, v[168:169]
	v_lshl_add_u64 v[2:3], s[76:77], 0, v[168:169]
	s_mov_b64 s[0:1], 0x1280000
	v_lshl_or_b32 v7, v1, 13, v5
	v_xor_b32_e32 v10, v6, v9
	v_bitop3_b32 v6, v6, v9, 4 bitop3:0x36
	v_lshl_add_u64 v[174:175], v[2:3], 0, s[0:1]
	v_lshrrev_b32_e32 v2, 4, v0
	v_add_u32_e32 v7, 16, v7
	v_lshlrev_b32_e32 v9, 4, v10
	v_lshlrev_b32_e32 v6, 4, v6
	s_abs_i32 s37, s26
	v_xor_b32_e32 v2, v2, v0
	v_add_u32_e32 v206, v7, v9
	v_add_u32_e32 v208, v7, v6
	v_cvt_f32_u32_e32 v7, s37
	v_bfe_u32 v4, v0, 6, 1
	v_ashrrev_i32_e32 v203, 3, v0
	v_lshlrev_b32_e32 v2, 4, v2
	v_lshlrev_b32_e32 v3, 7, v203
	v_and_b32_e32 v2, 0x70, v2
	s_add_i32 s0, 16, 0x10000
	v_lshl_or_b32 v5, v4, 13, v5
	v_add3_u32 v205, s0, v3, v2
	v_writelane_b32 v252, s0, 29
	v_add_u32_e32 v8, s0, v5
	s_add_i32 s0, 16, 0x14000
	v_add3_u32 v204, 16, v3, v2
	v_add3_u32 v210, s0, v3, v2
	v_rcp_iflag_f32_e32 v3, v7
	v_lshlrev_b32_e32 v213, 6, v1
	v_writelane_b32 v252, s0, 30
	v_add_u32_e32 v2, s0, v5
	v_mul_f32_e32 v1, 0x4f7ffffe, v3
	v_cvt_u32_f32_e32 v1, v1
	s_sub_i32 s0, 0, s37
	v_and_b32_e32 v202, 63, v0
	v_and_b32_e32 v0, 7, v0
	v_readfirstlane_b32 s1, v1
	s_mul_i32 s0, s0, s1
	s_mul_hi_u32 s0, s1, s0
	v_lshlrev_b32_e32 v168, 4, v0
	s_add_i32 s31, s27, s29
	s_lshl_b32 s35, s34, 6
	v_add_u32_e32 v207, v8, v9
	v_add_u32_e32 v209, v8, v6
	v_add_u32_e32 v211, v2, v9
	v_add_u32_e32 v212, v2, v6
	v_lshlrev_b32_e32 v214, 6, v4
	s_ashr_i32 s38, s26, 31
	s_add_i32 s39, s1, s0
	v_lshl_add_u64 v[176:177], s[76:77], 0, v[168:169]
	s_mov_b64 s[0:1], 0
	s_mov_b64 s[8:9], 0x80080
	s_mov_b64 s[10:11], 0x80000
	s_mov_b64 s[12:13], 0x100
	s_movk_i32 s40, 0x2000
	s_mov_b64 s[14:15], 0x5000
	s_mov_b32 s41, 0x31000
	s_mov_b32 s42, 0x32000
	s_mov_b32 s43, 0x33000
	v_mov_b32_e32 v215, 0x3000
	v_mov_b32_e32 v216, 0xffffe000
	s_mov_b32 s44, s62
	s_mov_b32 s12, 0
	s_mov_b32 s13, 0x18000
	s_branch .LBB0_845

.LBB0_860:
	s_ashr_i32 s24, s48, 31
	s_lshr_b32 s24, s24, 29
	s_add_i32 s24, s48, s24
	s_and_b32 s25, s24, 0x1fffff8
	s_lshl_b32 s24, s24, 5
	s_sub_i32 s25, s48, s25
	s_and_b32 s48, s24, 0xffffff00
	v_add_u32_e32 v48, s48, v203
	v_ashrrev_i32_e32 v49, 31, v48
	v_lshlrev_b64 v[48:49], 13, v[48:49]
	v_lshl_add_u64 v[50:51], v[172:173], 0, v[48:49]
	s_lshl_b64 s[20:21], s[20:21], 1
	s_lshl_b32 s47, s25, 7
	v_lshl_add_u64 v[52:53], v[50:51], 0, s[20:21]
	v_add_u32_e32 v50, s47, v203
	v_ashrrev_i32_e32 v51, 31, v50
	v_lshlrev_b64 v[50:51], 13, v[50:51]
	v_lshl_add_u64 v[54:55], v[174:175], 0, v[50:51]
	s_xor_b64 s[0:1], s[0:1], -1
	v_writelane_b32 v250, s0, 4
	s_andn2_b64 vcc, exec, s[0:1]
	v_lshl_add_u64 v[54:55], v[54:55], 0, s[20:21]
	s_cbranch_vccnz .LBB0_862
	v_add_co_u32_e32 v4, vcc, 0x80000, v52
	s_nop 1
	v_addc_co_u32_e32 v5, vcc, 0, v53, vcc
	v_add_co_u32_e32 v8, vcc, 0x100000, v52
	s_nop 1
	v_addc_co_u32_e32 v9, vcc, 0, v53, vcc
	v_add_co_u32_e32 v12, vcc, 0x180000, v52
	s_nop 1
	v_addc_co_u32_e32 v13, vcc, 0, v53, vcc
	v_add_co_u32_e32 v24, vcc, 0x80000, v54
	s_nop 1
	v_addc_co_u32_e32 v25, vcc, 0, v55, vcc
	s_nop 0
	s_nop 0
	s_nop 0
	s_nop 0
	s_nop 0
	s_nop 0
	s_nop 0
.LBB0_862:
	s_ashr_i32 s0, s50, 31
	s_lshr_b32 s0, s0, 29
	s_add_i32 s0, s50, s0
	s_lshl_b32 s1, s0, 5
	s_and_b32 s1, s1, 0xffffff00
	s_and_b32 s0, s0, 0x1fffff8
	v_add_u32_e32 v56, s1, v203
	s_sub_i32 s0, s50, s0
	v_ashrrev_i32_e32 v57, 31, v56
	v_lshl_add_u32 v58, s0, 7, v203
	v_lshlrev_b64 v[56:57], 13, v[56:57]
	v_ashrrev_i32_e32 v59, 31, v58
	v_lshl_add_u64 v[56:57], v[172:173], 0, v[56:57]
	v_lshlrev_b64 v[58:59], 13, v[58:59]
	s_lshl_b32 s98, s1, 13
	s_lshl_b32 s100, s0, 20
	s_lshl_b64 s[0:1], s[22:23], 1
	s_add_u32 s98, s98, s0
	s_add_u32 s98, s76, s98
	s_addc_u32 s99, s77, 0
	s_add_u32 s98, s98, 0x4900000
	s_addc_u32 s99, s99, 0
	s_add_u32 s100, s100, s0
	s_add_u32 s100, s76, s100
	s_addc_u32 s101, s77, 0
	s_add_u32 s100, s100, 0x1280000
	s_addc_u32 s101, s101, 0
	v_writelane_b32 v250, s98, 0
	v_writelane_b32 v250, s99, 1
	v_writelane_b32 v250, s100, 2
	v_writelane_b32 v250, s101, 3
	v_lshl_add_u64 v[58:59], v[174:175], 0, v[58:59]
	v_lshl_add_u64 v[178:179], v[56:57], 0, s[0:1]
	v_cndmask_b32_e64 v56, 0, 1, s[16:17]
	v_lshl_add_u64 v[180:181], v[58:59], 0, s[0:1]
	s_mov_b64 s[22:23], -1
	s_cmp_lt_u32 s49, 3
	v_cmp_ne_u32_e64 s[0:1], 1, v56
	s_cbranch_scc0 .LBB0_886
	s_and_b64 vcc, exec, s[0:1]
	s_cbranch_vccnz .LBB0_865
	v_add_co_u32_e32 v20, vcc, 0x80000, v178
	s_nop 1
	v_addc_co_u32_e32 v21, vcc, 0, v179, vcc
	v_add_co_u32_e32 v28, vcc, 0x100000, v178
	s_nop 1
	v_addc_co_u32_e32 v29, vcc, 0, v179, vcc
	v_add_co_u32_e32 v40, vcc, 0x180000, v178
	s_nop 0
	v_addc_co_u32_e32 v41, vcc, 0, v179, vcc
	v_add_co_u32_e32 v44, vcc, 0x80000, v180
	v_addc_co_u32_e32 v45, vcc, 0, v181, vcc
	s_nop 0

.LBB0_867:
	s_mov_b64 s[22:23], 0x100080
	v_lshl_add_u64 v[184:185], v[178:179], 0, s[22:23]
	s_mov_b64 s[22:23], 0x180080
	v_lshl_add_u64 v[186:187], v[178:179], 0, s[22:23]
	s_mov_b64 s[22:23], 0x100000
	v_lshl_add_u64 v[192:193], v[178:179], 0, s[22:23]
	s_mov_b64 s[22:23], 0x180000
	v_lshl_add_u64 v[198:199], v[176:177], 0, v[48:49]
	v_mov_b32_e32 v48, 0
	v_lshl_add_u64 v[182:183], v[178:179], 0, s[8:9]
	v_lshl_add_u64 v[188:189], v[180:181], 0, s[8:9]
	v_lshl_add_u64 v[190:191], v[178:179], 0, s[10:11]
	v_lshl_add_u64 v[194:195], v[178:179], 0, s[22:23]
	v_lshl_add_u64 v[196:197], v[180:181], 0, s[10:11]
	v_lshl_add_u64 v[200:201], v[176:177], 0, v[50:51]
	s_mov_b32 s24, 0
	v_mov_b32_e32 v49, v48
	v_mov_b32_e32 v50, v48
	v_mov_b32_e32 v51, v48
	v_mov_b32_e32 v52, v48
	v_mov_b32_e32 v53, v48
	v_mov_b32_e32 v54, v48
	v_mov_b32_e32 v55, v48
	v_mov_b32_e32 v56, v48
	v_mov_b32_e32 v57, v48
	v_mov_b32_e32 v58, v48
	v_mov_b32_e32 v59, v48
	v_mov_b32_e32 v60, v48
	v_mov_b32_e32 v61, v48
	v_mov_b32_e32 v62, v48
	v_mov_b32_e32 v63, v48
	v_mov_b32_e32 v64, v48
	v_mov_b32_e32 v65, v48
	v_mov_b32_e32 v66, v48
	v_mov_b32_e32 v67, v48
	v_mov_b32_e32 v68, v48
	v_mov_b32_e32 v69, v48
	v_mov_b32_e32 v70, v48
	v_mov_b32_e32 v71, v48
	v_mov_b32_e32 v72, v48
	v_mov_b32_e32 v73, v48
	v_mov_b32_e32 v74, v48
	v_mov_b32_e32 v75, v48
	v_mov_b32_e32 v76, v48
	v_mov_b32_e32 v77, v48
	v_mov_b32_e32 v78, v48
	v_mov_b32_e32 v79, v48
	v_mov_b32_e32 v80, v48
	v_mov_b32_e32 v81, v48
	v_mov_b32_e32 v82, v48
	v_mov_b32_e32 v83, v48
	v_mov_b32_e32 v84, v48
	v_mov_b32_e32 v85, v48
	v_mov_b32_e32 v86, v48
	v_mov_b32_e32 v87, v48
	v_mov_b32_e32 v88, v48
	v_mov_b32_e32 v89, v48
	v_mov_b32_e32 v90, v48
	v_mov_b32_e32 v91, v48
	v_mov_b32_e32 v92, v48
	v_mov_b32_e32 v93, v48
	v_mov_b32_e32 v94, v48
	v_mov_b32_e32 v95, v48
	v_mov_b32_e32 v96, v48
	v_mov_b32_e32 v97, v48
	v_mov_b32_e32 v98, v48
	v_mov_b32_e32 v99, v48
	v_mov_b32_e32 v100, v48
	v_mov_b32_e32 v101, v48
	v_mov_b32_e32 v102, v48
	v_mov_b32_e32 v103, v48
	v_mov_b32_e32 v104, v48
	v_mov_b32_e32 v105, v48
	v_mov_b32_e32 v106, v48
	v_mov_b32_e32 v107, v48
	v_mov_b32_e32 v108, v48
	v_mov_b32_e32 v109, v48
	v_mov_b32_e32 v110, v48
	v_mov_b32_e32 v111, v48
	v_lshrrev_b32_e32 v7, 1, v203
	v_and_b32_e32 v6, 7, v202
	v_xor_b32_e32 v7, v7, v6
	v_and_b32_e32 v7, 7, v7
	v_lshlrev_b32_e32 v7, 4, v7
	v_lshl_add_u32 v0, v203, 13, v7
	v_add_u32_e32 v1, 0x80000, v0
	v_add_u32_e32 v2, 0x100000, v0
	v_add_u32_e32 v3, 0x180000, v0
	v_mov_b32_e32 v4, v0
	v_add_u32_e32 v5, 0x80000, v4
	v_lshrrev_b32_e32 v6, 3, v203
	v_lshl_add_u32 v6, v6, 10, 16
	v_add_u32_e32 v10, 0xffff8000, v207
	v_add_u32_e32 v11, 0xffff8000, v209
	v_readlane_b32 vcc_hi, v250, 4
	s_lshl_b32 s98, s48, 13
	s_add_u32 s98, s98, s20
	s_add_u32 s98, s76, s98
	s_addc_u32 s99, s77, 0
	s_add_u32 s98, s98, 0x4900000
	s_addc_u32 s99, s99, 0
	s_lshl_b32 s100, s47, 13
	s_add_u32 s100, s100, s20
	s_add_u32 s100, s76, s100
	s_addc_u32 s101, s77, 0
	s_add_u32 s100, s100, 0x1280000
	s_addc_u32 s101, s101, 0
	s_cmp_eq_u32 vcc_hi, 0
	s_cbranch_scc1 .Lmys_primed
	v_readfirstlane_b32 vcc_lo, v6
	s_nop 0
	s_add_u32 vcc_lo, vcc_lo, s12
	s_mov_b32 m0, vcc_lo
	s_nop 0
	global_load_lds_dwordx4 v0, s[98:99]
	s_add_u32 m0, m0, 0x2000
	s_nop 0
	global_load_lds_dwordx4 v1, s[98:99]
	s_add_u32 m0, m0, 0x2000
	s_nop 0
	global_load_lds_dwordx4 v2, s[98:99]
	s_add_u32 m0, m0, 0x2000
	s_nop 0
	global_load_lds_dwordx4 v3, s[98:99]
	s_add_u32 m0, vcc_lo, 0x8000
	s_nop 0
	global_load_lds_dwordx4 v4, s[100:101]
	s_add_u32 m0, m0, 0x2000
	s_nop 0
	global_load_lds_dwordx4 v5, s[100:101]
	s_add_u32 s98, s98, 0x80
	s_addc_u32 s99, s99, 0
	s_add_u32 s100, s100, 0x80
	s_addc_u32 s101, s101, 0
	s_add_u32 vcc_hi, s12, 0xc000
	s_sub_u32 vcc_lo, vcc_hi, 0x24000
	s_cselect_b32 vcc_hi, vcc_hi, vcc_lo
	v_readfirstlane_b32 vcc_lo, v6
	s_nop 0
	s_add_u32 vcc_lo, vcc_lo, vcc_hi
	s_mov_b32 m0, vcc_lo
	s_nop 0
	global_load_lds_dwordx4 v0, s[98:99]
	s_add_u32 m0, m0, 0x2000
	s_nop 0
	global_load_lds_dwordx4 v1, s[98:99]
	s_add_u32 m0, m0, 0x2000
	s_nop 0
	global_load_lds_dwordx4 v2, s[98:99]
	s_add_u32 m0, m0, 0x2000
	s_nop 0
	global_load_lds_dwordx4 v3, s[98:99]
	s_add_u32 m0, vcc_lo, 0x8000
	s_nop 0
	global_load_lds_dwordx4 v4, s[100:101]
	s_add_u32 m0, m0, 0x2000
	s_nop 0
	global_load_lds_dwordx4 v5, s[100:101]
	s_add_u32 s98, s98, 0x80
	s_addc_u32 s99, s99, 0
	s_add_u32 s100, s100, 0x80
	s_addc_u32 s101, s101, 0
	s_branch .LBB0_868

.LBB0_868:
	v_add_u32_e32 v12, s12, v206
	v_add_u32_e32 v13, s12, v10
	v_add_u32_e32 v14, s12, v208
	v_add_u32_e32 v15, s12, v11
	v_readfirstlane_b32 vcc_lo, v6
	s_nop 0
	s_add_u32 vcc_lo, vcc_lo, s13
	s_waitcnt vmcnt(6) lgkmcnt(0)
	s_barrier
	ds_read_b128 v[112:115], v12
	ds_read_b128 v[116:119], v12 offset:2048
	ds_read_b128 v[120:123], v12 offset:4096
	ds_read_b128 v[124:127], v12 offset:6144
	ds_read_b128 v[128:131], v13
	ds_read_b128 v[132:135], v13 offset:2048
	ds_read_b128 v[136:139], v13 offset:4096
	ds_read_b128 v[140:143], v13 offset:6144
	s_mov_b32 m0, vcc_lo
	s_nop 0
	global_load_lds_dwordx4 v0, s[98:99]
	s_add_u32 m0, m0, 0x2000
	s_nop 0
	global_load_lds_dwordx4 v1, s[98:99]
	s_add_u32 m0, m0, 0x2000
	s_nop 0
	global_load_lds_dwordx4 v2, s[98:99]
	s_add_u32 m0, m0, 0x2000
	s_nop 0
	global_load_lds_dwordx4 v3, s[98:99]
	s_add_u32 m0, vcc_lo, 0x8000
	s_nop 0
	global_load_lds_dwordx4 v4, s[100:101]
	s_add_u32 m0, m0, 0x2000
	s_nop 0
	global_load_lds_dwordx4 v5, s[100:101]
	s_add_u32 s98, s98, 0x80
	s_addc_u32 s99, s99, 0
	s_add_u32 s100, s100, 0x80
	s_addc_u32 s101, s101, 0
	s_waitcnt lgkmcnt(0)
	v_mfma_f32_16x16x32_bf16 v[108:111], v[112:115], v[128:131], v[108:111]
	ds_read_b128 v[144:147], v14
	v_mfma_f32_16x16x32_bf16 v[104:107], v[112:115], v[132:135], v[104:107]
	ds_read_b128 v[148:151], v14 offset:2048
	v_mfma_f32_16x16x32_bf16 v[100:103], v[112:115], v[136:139], v[100:103]
	ds_read_b128 v[152:155], v14 offset:4096
	v_mfma_f32_16x16x32_bf16 v[96:99], v[112:115], v[140:143], v[96:99]
	ds_read_b128 v[156:159], v14 offset:6144
	v_mfma_f32_16x16x32_bf16 v[92:95], v[116:119], v[128:131], v[92:95]
	ds_read_b128 v[160:163], v15
	v_mfma_f32_16x16x32_bf16 v[88:91], v[116:119], v[132:135], v[88:91]
	ds_read_b128 v[164:167], v15 offset:2048
	v_mfma_f32_16x16x32_bf16 v[84:87], v[116:119], v[136:139], v[84:87]
	ds_read_b128 v[218:221], v15 offset:4096
	v_mfma_f32_16x16x32_bf16 v[80:83], v[116:119], v[140:143], v[80:83]
	ds_read_b128 v[228:231], v15 offset:6144
	v_mfma_f32_16x16x32_bf16 v[76:79], v[120:123], v[128:131], v[76:79]
	v_mfma_f32_16x16x32_bf16 v[72:75], v[120:123], v[132:135], v[72:75]
	v_mfma_f32_16x16x32_bf16 v[68:71], v[120:123], v[136:139], v[68:71]
	v_mfma_f32_16x16x32_bf16 v[64:67], v[120:123], v[140:143], v[64:67]
	v_mfma_f32_16x16x32_bf16 v[60:63], v[124:127], v[128:131], v[60:63]
	v_mfma_f32_16x16x32_bf16 v[56:59], v[124:127], v[132:135], v[56:59]
	v_mfma_f32_16x16x32_bf16 v[52:55], v[124:127], v[136:139], v[52:55]
	v_mfma_f32_16x16x32_bf16 v[48:51], v[124:127], v[140:143], v[48:51]
	s_mov_b32 s13, s12
	s_add_u32 s12, s12, 0xc000
	s_sub_u32 vcc_lo, s12, 0x24000
	s_cselect_b32 s12, s12, vcc_lo
	s_mov_b32 s24, 1
.Lmys_steady:
	v_add_u32_e32 v12, s12, v206
	v_add_u32_e32 v13, s12, v10
	v_add_u32_e32 v14, s12, v208
	v_add_u32_e32 v15, s12, v11
	v_readfirstlane_b32 vcc_lo, v6
	s_nop 0
	s_add_u32 vcc_lo, vcc_lo, s13
	s_waitcnt vmcnt(6) lgkmcnt(0)
	s_barrier
	v_mfma_f32_16x16x32_bf16 v[108:111], v[144:147], v[160:163], v[108:111]
	ds_read_b128 v[112:115], v12
	v_mfma_f32_16x16x32_bf16 v[104:107], v[144:147], v[164:167], v[104:107]
	ds_read_b128 v[116:119], v12 offset:2048
	v_mfma_f32_16x16x32_bf16 v[100:103], v[144:147], v[218:221], v[100:103]
	ds_read_b128 v[120:123], v12 offset:4096
	s_mov_b32 m0, vcc_lo
	v_mfma_f32_16x16x32_bf16 v[96:99], v[144:147], v[228:231], v[96:99]
	ds_read_b128 v[124:127], v12 offset:6144
	global_load_lds_dwordx4 v0, s[98:99]
	s_add_u32 m0, m0, 0x2000
	v_mfma_f32_16x16x32_bf16 v[92:95], v[148:151], v[160:163], v[92:95]
	ds_read_b128 v[128:131], v13
	global_load_lds_dwordx4 v1, s[98:99]
	s_add_u32 m0, m0, 0x2000
	v_mfma_f32_16x16x32_bf16 v[88:91], v[148:151], v[164:167], v[88:91]
	ds_read_b128 v[132:135], v13 offset:2048
	global_load_lds_dwordx4 v2, s[98:99]
	s_add_u32 m0, m0, 0x2000
	v_mfma_f32_16x16x32_bf16 v[84:87], v[148:151], v[218:221], v[84:87]
	ds_read_b128 v[136:139], v13 offset:4096
	global_load_lds_dwordx4 v3, s[98:99]
	s_add_u32 m0, vcc_lo, 0x8000
	v_mfma_f32_16x16x32_bf16 v[80:83], v[148:151], v[228:231], v[80:83]
	ds_read_b128 v[140:143], v13 offset:6144
	global_load_lds_dwordx4 v4, s[100:101]
	s_add_u32 m0, m0, 0x2000
	v_mfma_f32_16x16x32_bf16 v[76:79], v[152:155], v[160:163], v[76:79]
	global_load_lds_dwordx4 v5, s[100:101]
	v_mfma_f32_16x16x32_bf16 v[72:75], v[152:155], v[164:167], v[72:75]
	s_add_u32 s98, s98, 0x80
	s_addc_u32 s99, s99, 0
	s_add_u32 s100, s100, 0x80
	s_addc_u32 s101, s101, 0
	v_mfma_f32_16x16x32_bf16 v[68:71], v[152:155], v[218:221], v[68:71]
	v_mfma_f32_16x16x32_bf16 v[64:67], v[152:155], v[228:231], v[64:67]
	v_mfma_f32_16x16x32_bf16 v[60:63], v[156:159], v[160:163], v[60:63]
	v_mfma_f32_16x16x32_bf16 v[56:59], v[156:159], v[164:167], v[56:59]
	v_mfma_f32_16x16x32_bf16 v[52:55], v[156:159], v[218:221], v[52:55]
	v_mfma_f32_16x16x32_bf16 v[48:51], v[156:159], v[228:231], v[48:51]
	s_waitcnt lgkmcnt(0)
	v_mfma_f32_16x16x32_bf16 v[108:111], v[112:115], v[128:131], v[108:111]
	ds_read_b128 v[144:147], v14
	v_mfma_f32_16x16x32_bf16 v[104:107], v[112:115], v[132:135], v[104:107]
	ds_read_b128 v[148:151], v14 offset:2048
	v_mfma_f32_16x16x32_bf16 v[100:103], v[112:115], v[136:139], v[100:103]
	ds_read_b128 v[152:155], v14 offset:4096
	v_mfma_f32_16x16x32_bf16 v[96:99], v[112:115], v[140:143], v[96:99]
	ds_read_b128 v[156:159], v14 offset:6144
	v_mfma_f32_16x16x32_bf16 v[92:95], v[116:119], v[128:131], v[92:95]
	ds_read_b128 v[160:163], v15
	v_mfma_f32_16x16x32_bf16 v[88:91], v[116:119], v[132:135], v[88:91]
	ds_read_b128 v[164:167], v15 offset:2048
	v_mfma_f32_16x16x32_bf16 v[84:87], v[116:119], v[136:139], v[84:87]
	ds_read_b128 v[218:221], v15 offset:4096
	v_mfma_f32_16x16x32_bf16 v[80:83], v[116:119], v[140:143], v[80:83]
	ds_read_b128 v[228:231], v15 offset:6144
	v_mfma_f32_16x16x32_bf16 v[76:79], v[120:123], v[128:131], v[76:79]
	v_mfma_f32_16x16x32_bf16 v[72:75], v[120:123], v[132:135], v[72:75]
	v_mfma_f32_16x16x32_bf16 v[68:71], v[120:123], v[136:139], v[68:71]
	v_mfma_f32_16x16x32_bf16 v[64:67], v[120:123], v[140:143], v[64:67]
	v_mfma_f32_16x16x32_bf16 v[60:63], v[124:127], v[128:131], v[60:63]
	v_mfma_f32_16x16x32_bf16 v[56:59], v[124:127], v[132:135], v[56:59]
	v_mfma_f32_16x16x32_bf16 v[52:55], v[124:127], v[136:139], v[52:55]
	v_mfma_f32_16x16x32_bf16 v[48:51], v[124:127], v[140:143], v[48:51]
	s_mov_b32 s13, s12
	s_add_u32 s12, s12, 0xc000
	s_sub_u32 vcc_lo, s12, 0x24000
	s_cselect_b32 s12, s12, vcc_lo
	s_add_i32 s24, s24, 1
	s_sub_u32 vcc_hi, s49, 2
	s_cmp_lt_u32 s24, vcc_hi
	s_cbranch_scc1 .Lmys_steady
	s_and_b64 vcc, exec, s[0:1]
	s_cbranch_vccnz .Lmys_prelast_n
	v_readlane_b32 s98, v250, 0
	v_readlane_b32 s99, v250, 1
	v_readlane_b32 s100, v250, 2
	v_readlane_b32 s101, v250, 3
	v_add_u32_e32 v12, s12, v206
	v_add_u32_e32 v13, s12, v10
	v_add_u32_e32 v14, s12, v208
	v_add_u32_e32 v15, s12, v11
	v_readfirstlane_b32 vcc_lo, v6
	s_nop 0
	s_add_u32 vcc_lo, vcc_lo, s13
	s_waitcnt vmcnt(6) lgkmcnt(0)
	s_barrier
	v_mfma_f32_16x16x32_bf16 v[108:111], v[144:147], v[160:163], v[108:111]
	ds_read_b128 v[112:115], v12
	v_mfma_f32_16x16x32_bf16 v[104:107], v[144:147], v[164:167], v[104:107]
	ds_read_b128 v[116:119], v12 offset:2048
	v_mfma_f32_16x16x32_bf16 v[100:103], v[144:147], v[218:221], v[100:103]
	ds_read_b128 v[120:123], v12 offset:4096
	s_mov_b32 m0, vcc_lo
	v_mfma_f32_16x16x32_bf16 v[96:99], v[144:147], v[228:231], v[96:99]
	ds_read_b128 v[124:127], v12 offset:6144
	global_load_lds_dwordx4 v0, s[98:99]
	s_add_u32 m0, m0, 0x2000
	v_mfma_f32_16x16x32_bf16 v[92:95], v[148:151], v[160:163], v[92:95]
	ds_read_b128 v[128:131], v13
	global_load_lds_dwordx4 v1, s[98:99]
	s_add_u32 m0, m0, 0x2000
	v_mfma_f32_16x16x32_bf16 v[88:91], v[148:151], v[164:167], v[88:91]
	ds_read_b128 v[132:135], v13 offset:2048
	global_load_lds_dwordx4 v2, s[98:99]
	s_add_u32 m0, m0, 0x2000
	v_mfma_f32_16x16x32_bf16 v[84:87], v[148:151], v[218:221], v[84:87]
	ds_read_b128 v[136:139], v13 offset:4096
	global_load_lds_dwordx4 v3, s[98:99]
	s_add_u32 m0, vcc_lo, 0x8000
	v_mfma_f32_16x16x32_bf16 v[80:83], v[148:151], v[228:231], v[80:83]
	ds_read_b128 v[140:143], v13 offset:6144
	global_load_lds_dwordx4 v4, s[100:101]
	s_add_u32 m0, m0, 0x2000
	v_mfma_f32_16x16x32_bf16 v[76:79], v[152:155], v[160:163], v[76:79]
	global_load_lds_dwordx4 v5, s[100:101]
	v_mfma_f32_16x16x32_bf16 v[72:75], v[152:155], v[164:167], v[72:75]
	s_add_u32 s98, s98, 0x80
	s_addc_u32 s99, s99, 0
	s_add_u32 s100, s100, 0x80
	s_addc_u32 s101, s101, 0
	v_mfma_f32_16x16x32_bf16 v[68:71], v[152:155], v[218:221], v[68:71]
	v_mfma_f32_16x16x32_bf16 v[64:67], v[152:155], v[228:231], v[64:67]
	v_mfma_f32_16x16x32_bf16 v[60:63], v[156:159], v[160:163], v[60:63]
	v_mfma_f32_16x16x32_bf16 v[56:59], v[156:159], v[164:167], v[56:59]
	v_mfma_f32_16x16x32_bf16 v[52:55], v[156:159], v[218:221], v[52:55]
	v_mfma_f32_16x16x32_bf16 v[48:51], v[156:159], v[228:231], v[48:51]
	s_waitcnt lgkmcnt(0)
	v_mfma_f32_16x16x32_bf16 v[108:111], v[112:115], v[128:131], v[108:111]
	ds_read_b128 v[144:147], v14
	v_mfma_f32_16x16x32_bf16 v[104:107], v[112:115], v[132:135], v[104:107]
	ds_read_b128 v[148:151], v14 offset:2048
	v_mfma_f32_16x16x32_bf16 v[100:103], v[112:115], v[136:139], v[100:103]
	ds_read_b128 v[152:155], v14 offset:4096
	v_mfma_f32_16x16x32_bf16 v[96:99], v[112:115], v[140:143], v[96:99]
	ds_read_b128 v[156:159], v14 offset:6144
	v_mfma_f32_16x16x32_bf16 v[92:95], v[116:119], v[128:131], v[92:95]
	ds_read_b128 v[160:163], v15
	v_mfma_f32_16x16x32_bf16 v[88:91], v[116:119], v[132:135], v[88:91]
	ds_read_b128 v[164:167], v15 offset:2048
	v_mfma_f32_16x16x32_bf16 v[84:87], v[116:119], v[136:139], v[84:87]
	ds_read_b128 v[218:221], v15 offset:4096
	v_mfma_f32_16x16x32_bf16 v[80:83], v[116:119], v[140:143], v[80:83]
	ds_read_b128 v[228:231], v15 offset:6144
	v_mfma_f32_16x16x32_bf16 v[76:79], v[120:123], v[128:131], v[76:79]
	v_mfma_f32_16x16x32_bf16 v[72:75], v[120:123], v[132:135], v[72:75]
	v_mfma_f32_16x16x32_bf16 v[68:71], v[120:123], v[136:139], v[68:71]
	v_mfma_f32_16x16x32_bf16 v[64:67], v[120:123], v[140:143], v[64:67]
	v_mfma_f32_16x16x32_bf16 v[60:63], v[124:127], v[128:131], v[60:63]
	v_mfma_f32_16x16x32_bf16 v[56:59], v[124:127], v[132:135], v[56:59]
	v_mfma_f32_16x16x32_bf16 v[52:55], v[124:127], v[136:139], v[52:55]
	v_mfma_f32_16x16x32_bf16 v[48:51], v[124:127], v[140:143], v[48:51]
	s_mov_b32 s13, s12
	s_add_u32 s12, s12, 0xc000
	s_sub_u32 vcc_lo, s12, 0x24000
	s_cselect_b32 s12, s12, vcc_lo
	v_add_u32_e32 v12, s12, v206
	v_add_u32_e32 v13, s12, v10
	v_add_u32_e32 v14, s12, v208
	v_add_u32_e32 v15, s12, v11
	v_readfirstlane_b32 vcc_lo, v6
	s_nop 0
	s_add_u32 vcc_lo, vcc_lo, s13
	s_waitcnt vmcnt(6) lgkmcnt(0)
	s_barrier
	v_mfma_f32_16x16x32_bf16 v[108:111], v[144:147], v[160:163], v[108:111]
	ds_read_b128 v[112:115], v12
	v_mfma_f32_16x16x32_bf16 v[104:107], v[144:147], v[164:167], v[104:107]
	ds_read_b128 v[116:119], v12 offset:2048
	v_mfma_f32_16x16x32_bf16 v[100:103], v[144:147], v[218:221], v[100:103]
	ds_read_b128 v[120:123], v12 offset:4096
	s_mov_b32 m0, vcc_lo
	v_mfma_f32_16x16x32_bf16 v[96:99], v[144:147], v[228:231], v[96:99]
	ds_read_b128 v[124:127], v12 offset:6144
	global_load_lds_dwordx4 v0, s[98:99]
	s_add_u32 m0, m0, 0x2000
	v_mfma_f32_16x16x32_bf16 v[92:95], v[148:151], v[160:163], v[92:95]
	ds_read_b128 v[128:131], v13
	global_load_lds_dwordx4 v1, s[98:99]
	s_add_u32 m0, m0, 0x2000
	v_mfma_f32_16x16x32_bf16 v[88:91], v[148:151], v[164:167], v[88:91]
	ds_read_b128 v[132:135], v13 offset:2048
	global_load_lds_dwordx4 v2, s[98:99]
	s_add_u32 m0, m0, 0x2000
	v_mfma_f32_16x16x32_bf16 v[84:87], v[148:151], v[218:221], v[84:87]
	ds_read_b128 v[136:139], v13 offset:4096
	global_load_lds_dwordx4 v3, s[98:99]
	s_add_u32 m0, vcc_lo, 0x8000
	v_mfma_f32_16x16x32_bf16 v[80:83], v[148:151], v[228:231], v[80:83]
	ds_read_b128 v[140:143], v13 offset:6144
	global_load_lds_dwordx4 v4, s[100:101]
	s_add_u32 m0, m0, 0x2000
	v_mfma_f32_16x16x32_bf16 v[76:79], v[152:155], v[160:163], v[76:79]
	global_load_lds_dwordx4 v5, s[100:101]
	v_mfma_f32_16x16x32_bf16 v[72:75], v[152:155], v[164:167], v[72:75]
	s_add_u32 s98, s98, 0x80
	s_addc_u32 s99, s99, 0
	s_add_u32 s100, s100, 0x80
	s_addc_u32 s101, s101, 0
	v_mfma_f32_16x16x32_bf16 v[68:71], v[152:155], v[218:221], v[68:71]
	v_mfma_f32_16x16x32_bf16 v[64:67], v[152:155], v[228:231], v[64:67]
	v_mfma_f32_16x16x32_bf16 v[60:63], v[156:159], v[160:163], v[60:63]
	v_mfma_f32_16x16x32_bf16 v[56:59], v[156:159], v[164:167], v[56:59]
	v_mfma_f32_16x16x32_bf16 v[52:55], v[156:159], v[218:221], v[52:55]
	v_mfma_f32_16x16x32_bf16 v[48:51], v[156:159], v[228:231], v[48:51]
	s_waitcnt lgkmcnt(0)
	v_mfma_f32_16x16x32_bf16 v[108:111], v[112:115], v[128:131], v[108:111]
	ds_read_b128 v[144:147], v14
	v_mfma_f32_16x16x32_bf16 v[104:107], v[112:115], v[132:135], v[104:107]
	ds_read_b128 v[148:151], v14 offset:2048
	v_mfma_f32_16x16x32_bf16 v[100:103], v[112:115], v[136:139], v[100:103]
	ds_read_b128 v[152:155], v14 offset:4096
	v_mfma_f32_16x16x32_bf16 v[96:99], v[112:115], v[140:143], v[96:99]
	ds_read_b128 v[156:159], v14 offset:6144
	v_mfma_f32_16x16x32_bf16 v[92:95], v[116:119], v[128:131], v[92:95]
	ds_read_b128 v[160:163], v15
	v_mfma_f32_16x16x32_bf16 v[88:91], v[116:119], v[132:135], v[88:91]
	ds_read_b128 v[164:167], v15 offset:2048
	v_mfma_f32_16x16x32_bf16 v[84:87], v[116:119], v[136:139], v[84:87]
	ds_read_b128 v[218:221], v15 offset:4096
	v_mfma_f32_16x16x32_bf16 v[80:83], v[116:119], v[140:143], v[80:83]
	ds_read_b128 v[228:231], v15 offset:6144
	v_mfma_f32_16x16x32_bf16 v[76:79], v[120:123], v[128:131], v[76:79]
	v_mfma_f32_16x16x32_bf16 v[72:75], v[120:123], v[132:135], v[72:75]
	v_mfma_f32_16x16x32_bf16 v[68:71], v[120:123], v[136:139], v[68:71]
	v_mfma_f32_16x16x32_bf16 v[64:67], v[120:123], v[140:143], v[64:67]
	v_mfma_f32_16x16x32_bf16 v[60:63], v[124:127], v[128:131], v[60:63]
	v_mfma_f32_16x16x32_bf16 v[56:59], v[124:127], v[132:135], v[56:59]
	v_mfma_f32_16x16x32_bf16 v[52:55], v[124:127], v[136:139], v[52:55]
	v_mfma_f32_16x16x32_bf16 v[48:51], v[124:127], v[140:143], v[48:51]
	s_mov_b32 s13, s12
	s_add_u32 s12, s12, 0xc000
	s_sub_u32 vcc_lo, s12, 0x24000
	s_cselect_b32 s12, s12, vcc_lo
	s_waitcnt lgkmcnt(0)
	v_mfma_f32_16x16x32_bf16 v[108:111], v[144:147], v[160:163], v[108:111]
	v_mfma_f32_16x16x32_bf16 v[104:107], v[144:147], v[164:167], v[104:107]
	v_mfma_f32_16x16x32_bf16 v[100:103], v[144:147], v[218:221], v[100:103]
	v_mfma_f32_16x16x32_bf16 v[96:99], v[144:147], v[228:231], v[96:99]
	v_mfma_f32_16x16x32_bf16 v[92:95], v[148:151], v[160:163], v[92:95]
	v_mfma_f32_16x16x32_bf16 v[88:91], v[148:151], v[164:167], v[88:91]
	v_mfma_f32_16x16x32_bf16 v[84:87], v[148:151], v[218:221], v[84:87]
	v_mfma_f32_16x16x32_bf16 v[80:83], v[148:151], v[228:231], v[80:83]
	v_mfma_f32_16x16x32_bf16 v[76:79], v[152:155], v[160:163], v[76:79]
	v_mfma_f32_16x16x32_bf16 v[72:75], v[152:155], v[164:167], v[72:75]
	v_mfma_f32_16x16x32_bf16 v[68:71], v[152:155], v[218:221], v[68:71]
	v_mfma_f32_16x16x32_bf16 v[64:67], v[152:155], v[228:231], v[64:67]
	v_mfma_f32_16x16x32_bf16 v[60:63], v[156:159], v[160:163], v[60:63]
	v_mfma_f32_16x16x32_bf16 v[56:59], v[156:159], v[164:167], v[56:59]
	v_mfma_f32_16x16x32_bf16 v[52:55], v[156:159], v[218:221], v[52:55]
	v_mfma_f32_16x16x32_bf16 v[48:51], v[156:159], v[228:231], v[48:51]
	s_and_b64 vcc, exec, s[22:23]
	s_nop 7
	s_branch .LBB0_889
.Lmys_prelast_n:
	v_add_u32_e32 v12, s12, v206
	v_add_u32_e32 v13, s12, v10
	v_add_u32_e32 v14, s12, v208
	v_add_u32_e32 v15, s12, v11
	s_waitcnt vmcnt(6) lgkmcnt(0)
	s_barrier
	v_mfma_f32_16x16x32_bf16 v[108:111], v[144:147], v[160:163], v[108:111]
	ds_read_b128 v[112:115], v12
	v_mfma_f32_16x16x32_bf16 v[104:107], v[144:147], v[164:167], v[104:107]
	ds_read_b128 v[116:119], v12 offset:2048
	v_mfma_f32_16x16x32_bf16 v[100:103], v[144:147], v[218:221], v[100:103]
	ds_read_b128 v[120:123], v12 offset:4096
	v_mfma_f32_16x16x32_bf16 v[96:99], v[144:147], v[228:231], v[96:99]
	ds_read_b128 v[124:127], v12 offset:6144
	v_mfma_f32_16x16x32_bf16 v[92:95], v[148:151], v[160:163], v[92:95]
	ds_read_b128 v[128:131], v13
	v_mfma_f32_16x16x32_bf16 v[88:91], v[148:151], v[164:167], v[88:91]
	ds_read_b128 v[132:135], v13 offset:2048
	v_mfma_f32_16x16x32_bf16 v[84:87], v[148:151], v[218:221], v[84:87]
	ds_read_b128 v[136:139], v13 offset:4096
	v_mfma_f32_16x16x32_bf16 v[80:83], v[148:151], v[228:231], v[80:83]
	ds_read_b128 v[140:143], v13 offset:6144
	v_mfma_f32_16x16x32_bf16 v[76:79], v[152:155], v[160:163], v[76:79]
	v_mfma_f32_16x16x32_bf16 v[72:75], v[152:155], v[164:167], v[72:75]
	v_mfma_f32_16x16x32_bf16 v[68:71], v[152:155], v[218:221], v[68:71]
	v_mfma_f32_16x16x32_bf16 v[64:67], v[152:155], v[228:231], v[64:67]
	v_mfma_f32_16x16x32_bf16 v[60:63], v[156:159], v[160:163], v[60:63]
	v_mfma_f32_16x16x32_bf16 v[56:59], v[156:159], v[164:167], v[56:59]
	v_mfma_f32_16x16x32_bf16 v[52:55], v[156:159], v[218:221], v[52:55]
	v_mfma_f32_16x16x32_bf16 v[48:51], v[156:159], v[228:231], v[48:51]
	s_waitcnt lgkmcnt(0)
	v_mfma_f32_16x16x32_bf16 v[108:111], v[112:115], v[128:131], v[108:111]
	ds_read_b128 v[144:147], v14
	v_mfma_f32_16x16x32_bf16 v[104:107], v[112:115], v[132:135], v[104:107]
	ds_read_b128 v[148:151], v14 offset:2048
	v_mfma_f32_16x16x32_bf16 v[100:103], v[112:115], v[136:139], v[100:103]
	ds_read_b128 v[152:155], v14 offset:4096
	v_mfma_f32_16x16x32_bf16 v[96:99], v[112:115], v[140:143], v[96:99]
	ds_read_b128 v[156:159], v14 offset:6144
	v_mfma_f32_16x16x32_bf16 v[92:95], v[116:119], v[128:131], v[92:95]
	ds_read_b128 v[160:163], v15
	v_mfma_f32_16x16x32_bf16 v[88:91], v[116:119], v[132:135], v[88:91]
	ds_read_b128 v[164:167], v15 offset:2048
	v_mfma_f32_16x16x32_bf16 v[84:87], v[116:119], v[136:139], v[84:87]
	ds_read_b128 v[218:221], v15 offset:4096
	v_mfma_f32_16x16x32_bf16 v[80:83], v[116:119], v[140:143], v[80:83]
	ds_read_b128 v[228:231], v15 offset:6144
	v_mfma_f32_16x16x32_bf16 v[76:79], v[120:123], v[128:131], v[76:79]
	v_mfma_f32_16x16x32_bf16 v[72:75], v[120:123], v[132:135], v[72:75]
	v_mfma_f32_16x16x32_bf16 v[68:71], v[120:123], v[136:139], v[68:71]
	v_mfma_f32_16x16x32_bf16 v[64:67], v[120:123], v[140:143], v[64:67]
	v_mfma_f32_16x16x32_bf16 v[60:63], v[124:127], v[128:131], v[60:63]
	v_mfma_f32_16x16x32_bf16 v[56:59], v[124:127], v[132:135], v[56:59]
	v_mfma_f32_16x16x32_bf16 v[52:55], v[124:127], v[136:139], v[52:55]
	v_mfma_f32_16x16x32_bf16 v[48:51], v[124:127], v[140:143], v[48:51]
	s_mov_b32 s13, s12
	s_add_u32 s12, s12, 0xc000
	s_sub_u32 vcc_lo, s12, 0x24000
	s_cselect_b32 s12, s12, vcc_lo
	v_add_u32_e32 v12, s12, v206
	v_add_u32_e32 v13, s12, v10
	v_add_u32_e32 v14, s12, v208
	v_add_u32_e32 v15, s12, v11
	s_waitcnt vmcnt(0) lgkmcnt(0)
	s_barrier
	v_mfma_f32_16x16x32_bf16 v[108:111], v[144:147], v[160:163], v[108:111]
	ds_read_b128 v[112:115], v12
	v_mfma_f32_16x16x32_bf16 v[104:107], v[144:147], v[164:167], v[104:107]
	ds_read_b128 v[116:119], v12 offset:2048
	v_mfma_f32_16x16x32_bf16 v[100:103], v[144:147], v[218:221], v[100:103]
	ds_read_b128 v[120:123], v12 offset:4096
	v_mfma_f32_16x16x32_bf16 v[96:99], v[144:147], v[228:231], v[96:99]
	ds_read_b128 v[124:127], v12 offset:6144
	v_mfma_f32_16x16x32_bf16 v[92:95], v[148:151], v[160:163], v[92:95]
	ds_read_b128 v[128:131], v13
	v_mfma_f32_16x16x32_bf16 v[88:91], v[148:151], v[164:167], v[88:91]
	ds_read_b128 v[132:135], v13 offset:2048
	v_mfma_f32_16x16x32_bf16 v[84:87], v[148:151], v[218:221], v[84:87]
	ds_read_b128 v[136:139], v13 offset:4096
	v_mfma_f32_16x16x32_bf16 v[80:83], v[148:151], v[228:231], v[80:83]
	ds_read_b128 v[140:143], v13 offset:6144
	v_mfma_f32_16x16x32_bf16 v[76:79], v[152:155], v[160:163], v[76:79]
	v_mfma_f32_16x16x32_bf16 v[72:75], v[152:155], v[164:167], v[72:75]
	v_mfma_f32_16x16x32_bf16 v[68:71], v[152:155], v[218:221], v[68:71]
	v_mfma_f32_16x16x32_bf16 v[64:67], v[152:155], v[228:231], v[64:67]
	v_mfma_f32_16x16x32_bf16 v[60:63], v[156:159], v[160:163], v[60:63]
	v_mfma_f32_16x16x32_bf16 v[56:59], v[156:159], v[164:167], v[56:59]
	v_mfma_f32_16x16x32_bf16 v[52:55], v[156:159], v[218:221], v[52:55]
	v_mfma_f32_16x16x32_bf16 v[48:51], v[156:159], v[228:231], v[48:51]
	s_waitcnt lgkmcnt(0)
	v_mfma_f32_16x16x32_bf16 v[108:111], v[112:115], v[128:131], v[108:111]
	ds_read_b128 v[144:147], v14
	v_mfma_f32_16x16x32_bf16 v[104:107], v[112:115], v[132:135], v[104:107]
	ds_read_b128 v[148:151], v14 offset:2048
	v_mfma_f32_16x16x32_bf16 v[100:103], v[112:115], v[136:139], v[100:103]
	ds_read_b128 v[152:155], v14 offset:4096
	v_mfma_f32_16x16x32_bf16 v[96:99], v[112:115], v[140:143], v[96:99]
	ds_read_b128 v[156:159], v14 offset:6144
	v_mfma_f32_16x16x32_bf16 v[92:95], v[116:119], v[128:131], v[92:95]
	ds_read_b128 v[160:163], v15
	v_mfma_f32_16x16x32_bf16 v[88:91], v[116:119], v[132:135], v[88:91]
	ds_read_b128 v[164:167], v15 offset:2048
	v_mfma_f32_16x16x32_bf16 v[84:87], v[116:119], v[136:139], v[84:87]
	ds_read_b128 v[218:221], v15 offset:4096
	v_mfma_f32_16x16x32_bf16 v[80:83], v[116:119], v[140:143], v[80:83]
	ds_read_b128 v[228:231], v15 offset:6144
	v_mfma_f32_16x16x32_bf16 v[76:79], v[120:123], v[128:131], v[76:79]
	v_mfma_f32_16x16x32_bf16 v[72:75], v[120:123], v[132:135], v[72:75]
	v_mfma_f32_16x16x32_bf16 v[68:71], v[120:123], v[136:139], v[68:71]
	v_mfma_f32_16x16x32_bf16 v[64:67], v[120:123], v[140:143], v[64:67]
	v_mfma_f32_16x16x32_bf16 v[60:63], v[124:127], v[128:131], v[60:63]
	v_mfma_f32_16x16x32_bf16 v[56:59], v[124:127], v[132:135], v[56:59]
	v_mfma_f32_16x16x32_bf16 v[52:55], v[124:127], v[136:139], v[52:55]
	v_mfma_f32_16x16x32_bf16 v[48:51], v[124:127], v[140:143], v[48:51]
	s_mov_b32 s13, s12
	s_add_u32 s12, s12, 0xc000
	s_sub_u32 vcc_lo, s12, 0x24000
	s_cselect_b32 s12, s12, vcc_lo
	s_waitcnt lgkmcnt(0)
	v_mfma_f32_16x16x32_bf16 v[108:111], v[144:147], v[160:163], v[108:111]
	v_mfma_f32_16x16x32_bf16 v[104:107], v[144:147], v[164:167], v[104:107]
	v_mfma_f32_16x16x32_bf16 v[100:103], v[144:147], v[218:221], v[100:103]
	v_mfma_f32_16x16x32_bf16 v[96:99], v[144:147], v[228:231], v[96:99]
	v_mfma_f32_16x16x32_bf16 v[92:95], v[148:151], v[160:163], v[92:95]
	v_mfma_f32_16x16x32_bf16 v[88:91], v[148:151], v[164:167], v[88:91]
	v_mfma_f32_16x16x32_bf16 v[84:87], v[148:151], v[218:221], v[84:87]
	v_mfma_f32_16x16x32_bf16 v[80:83], v[148:151], v[228:231], v[80:83]
	v_mfma_f32_16x16x32_bf16 v[76:79], v[152:155], v[160:163], v[76:79]
	v_mfma_f32_16x16x32_bf16 v[72:75], v[152:155], v[164:167], v[72:75]
	v_mfma_f32_16x16x32_bf16 v[68:71], v[152:155], v[218:221], v[68:71]
	v_mfma_f32_16x16x32_bf16 v[64:67], v[152:155], v[228:231], v[64:67]
	v_mfma_f32_16x16x32_bf16 v[60:63], v[156:159], v[160:163], v[60:63]
	v_mfma_f32_16x16x32_bf16 v[56:59], v[156:159], v[164:167], v[56:59]
	v_mfma_f32_16x16x32_bf16 v[52:55], v[156:159], v[218:221], v[52:55]
	v_mfma_f32_16x16x32_bf16 v[48:51], v[156:159], v[228:231], v[48:51]
	s_and_b64 vcc, exec, s[22:23]
	s_nop 7
	s_branch .LBB0_889

.LBB0_887:
	v_add_co_u32_e32 v20, vcc, 0x80000, v52
	s_nop 1
	v_addc_co_u32_e32 v21, vcc, 0, v53, vcc
	v_add_co_u32_e32 v28, vcc, 0x100000, v52
	s_nop 1
	v_addc_co_u32_e32 v29, vcc, 0, v53, vcc
	v_add_co_u32_e32 v40, vcc, 0x180000, v52
	s_nop 0
	v_addc_co_u32_e32 v41, vcc, 0, v53, vcc
	v_add_co_u32_e32 v44, vcc, 0x80000, v54
	v_addc_co_u32_e32 v45, vcc, 0, v55, vcc
	s_nop 0
	s_cmp_eq_u32 s49, 0
	s_cbranch_scc0 .LBB0_867
